# v16: hgrn_scan keeps 8 chunk steps of loads in flight per thread (was 2)
# baseline (speedup 1.0000x reference)
; DI void hgrn_scan(float* hst, const float* hdv, float* out, int gt, bool dry) {
;     const int bh = gt >> 12, rem = gt & 4095, w = rem >> 9, tile = (rem >> 6) & 7, lane = rem & 63;
;     const int d0 = 16 * tile + 4 * (lane >> 4), e = 16 * w + (lane & 15);
;     f32x4 S = {0.f, 0.f, 0.f, 0.f};
; #pragma unroll
;     for (int c = 0; c < 16; ++c) { const int item = bh * 16 + c; float* p = hst + (size_t)item * 16384 + (size_t)(w * 8 + tile) * 256 + lane * 4;
;         const f32x4 loc = *(const f32x4*)p; const f32x4 dv = *(const f32x4*)(hdv + (size_t)item * 128 + d0);
;         if (!dry) *(f32x4*)p = S; S = dv * S + loc; }
; #pragma unroll
;     for (int r = 0; r < 4; ++r) out[O_SP + ((size_t)bh * 128 + d0 + r) * 128 + e] = S[r];
; }
.LBB0_937:
	v_bfe_u32 v2, v13, 6, 3
	v_lshrrev_b32_e32 v5, 2, v13
	v_ashrrev_i32_e32 v4, 12, v13
	v_bfe_u32 v15, v13, 9, 3
	v_and_b32_e32 v5, 12, v5
	v_lshlrev_b32_e32 v7, 10, v2
	v_and_b32_e32 v11, 0xfc, v14
	v_lshlrev_b32_e32 v6, 4, v4
	v_lshl_or_b32 v58, v2, 4, v5
	v_lshl_or_b32 v2, v15, 13, v7
	v_lshl_add_u64 v[8:9], s[70:71], 0, v[2:3]
	v_lshlrev_b32_e32 v2, 2, v11
	v_ashrrev_i32_e32 v7, 31, v6
	v_lshl_add_u64 v[8:9], v[8:9], 0, v[2:3]
	v_lshlrev_b32_e32 v2, 2, v58
	v_lshlrev_b64 v[20:21], 16, v[6:7]
	v_lshlrev_b64 v[22:23], 9, v[6:7]
	v_lshl_add_u64 v[10:11], s[20:21], 0, v[2:3]
	v_lshl_add_u64 v[196:197], v[8:9], 0, v[20:21]
	v_lshl_add_u64 v[228:229], v[10:11], 0, v[22:23]
	s_mov_b64 s[14:15], 0x10000
	s_mov_b64 s[16:17], 0x1000
	v_lshl_add_u64 v[230:231], v[228:229], 0, s[16:17]
	global_load_dwordx4 v[130:133], v[196:197], off
	global_load_dwordx4 v[162:165], v[228:229], off
	v_lshl_add_u64 v[198:199], v[196:197], 0, s[14:15]
	global_load_dwordx4 v[134:137], v[198:199], off
	global_load_dwordx4 v[166:169], v[228:229], off offset:512
	v_lshl_add_u64 v[200:201], v[198:199], 0, s[14:15]
	global_load_dwordx4 v[138:141], v[200:201], off
	global_load_dwordx4 v[170:173], v[228:229], off offset:1024
	v_lshl_add_u64 v[202:203], v[200:201], 0, s[14:15]
	global_load_dwordx4 v[142:145], v[202:203], off
	global_load_dwordx4 v[174:177], v[228:229], off offset:1536
	v_lshl_add_u64 v[204:205], v[202:203], 0, s[14:15]
	global_load_dwordx4 v[146:149], v[204:205], off
	global_load_dwordx4 v[178:181], v[228:229], off offset:2048
	v_lshl_add_u64 v[206:207], v[204:205], 0, s[14:15]
	global_load_dwordx4 v[150:153], v[206:207], off
	global_load_dwordx4 v[184:187], v[228:229], off offset:2560
	v_lshl_add_u64 v[208:209], v[206:207], 0, s[14:15]
	global_load_dwordx4 v[154:157], v[208:209], off
	global_load_dwordx4 v[188:191], v[228:229], off offset:3072
	v_lshl_add_u64 v[210:211], v[208:209], 0, s[14:15]
	global_load_dwordx4 v[158:161], v[210:211], off
	global_load_dwordx4 v[192:195], v[228:229], off offset:3584
	v_lshl_add_u64 v[212:213], v[210:211], 0, s[14:15]
	v_lshl_add_u64 v[214:215], v[212:213], 0, s[14:15]
	v_lshl_add_u64 v[216:217], v[214:215], 0, s[14:15]
	v_lshl_add_u64 v[218:219], v[216:217], 0, s[14:15]
	v_lshl_add_u64 v[220:221], v[218:219], 0, s[14:15]
	v_lshl_add_u64 v[222:223], v[220:221], 0, s[14:15]
	v_lshl_add_u64 v[224:225], v[222:223], 0, s[14:15]
	v_lshl_add_u64 v[226:227], v[224:225], 0, s[14:15]
	v_ashrrev_i32_e32 v5, 31, v4
	v_lshlrev_b64 v[4:5], 16, v[4:5]
	v_lshl_add_u64 v[4:5], s[42:43], 0, v[4:5]
	v_lshlrev_b32_e32 v2, 9, v58
	v_add_u32_e32 v13, s10, v13
	v_lshl_add_u64 v[4:5], v[4:5], 0, v[2:3]
	v_lshl_or_b32 v2, v15, 6, v12
	v_cmp_lt_i32_e32 vcc, s13, v13
	v_lshl_add_u64 v[4:5], v[4:5], 0, v[2:3]
	s_or_b64 s[8:9], vcc, s[8:9]
	v_add_co_u32_e32 v4, vcc, s12, v4
	v_add_u32_e32 v14, s11, v14
	s_nop 0
	v_addc_co_u32_e32 v5, vcc, 0, v5, vcc
	s_waitcnt vmcnt(14)
	global_store_dwordx4 v[196:197], v[16:19], off
	v_pk_fma_f32 v[20:21], v[16:17], v[162:163], v[130:131]
	v_pk_fma_f32 v[22:23], v[18:19], v[164:165], v[132:133]
	global_load_dwordx4 v[130:133], v[212:213], off
	global_load_dwordx4 v[162:165], v[230:231], off
	s_waitcnt vmcnt(15)
	global_store_dwordx4 v[198:199], v[20:23], off
	v_pk_fma_f32 v[24:25], v[20:21], v[166:167], v[134:135]
	v_pk_fma_f32 v[26:27], v[22:23], v[168:169], v[136:137]
	global_load_dwordx4 v[134:137], v[214:215], off
	global_load_dwordx4 v[166:169], v[230:231], off offset:512
	s_waitcnt vmcnt(16)
	global_store_dwordx4 v[200:201], v[24:27], off
	v_pk_fma_f32 v[20:21], v[24:25], v[170:171], v[138:139]
	v_pk_fma_f32 v[22:23], v[26:27], v[172:173], v[140:141]
	global_load_dwordx4 v[138:141], v[216:217], off
	global_load_dwordx4 v[170:173], v[230:231], off offset:1024
	s_waitcnt vmcnt(17)
	global_store_dwordx4 v[202:203], v[20:23], off
	v_pk_fma_f32 v[24:25], v[20:21], v[174:175], v[142:143]
	v_pk_fma_f32 v[26:27], v[22:23], v[176:177], v[144:145]
	global_load_dwordx4 v[142:145], v[218:219], off
	global_load_dwordx4 v[174:177], v[230:231], off offset:1536
	s_waitcnt vmcnt(18)
	global_store_dwordx4 v[204:205], v[24:27], off
	v_pk_fma_f32 v[20:21], v[24:25], v[178:179], v[146:147]
	v_pk_fma_f32 v[22:23], v[26:27], v[180:181], v[148:149]
	global_load_dwordx4 v[146:149], v[220:221], off
	global_load_dwordx4 v[178:181], v[230:231], off offset:2048
	s_waitcnt vmcnt(19)
	global_store_dwordx4 v[206:207], v[20:23], off
	v_pk_fma_f32 v[24:25], v[20:21], v[184:185], v[150:151]
	v_pk_fma_f32 v[26:27], v[22:23], v[186:187], v[152:153]
	global_load_dwordx4 v[150:153], v[222:223], off
	global_load_dwordx4 v[184:187], v[230:231], off offset:2560
	s_waitcnt vmcnt(20)
	global_store_dwordx4 v[208:209], v[24:27], off
	v_pk_fma_f32 v[20:21], v[24:25], v[188:189], v[154:155]
	v_pk_fma_f32 v[22:23], v[26:27], v[190:191], v[156:157]
	global_load_dwordx4 v[154:157], v[224:225], off
	global_load_dwordx4 v[188:191], v[230:231], off offset:3072
	s_waitcnt vmcnt(21)
	global_store_dwordx4 v[210:211], v[20:23], off
	v_pk_fma_f32 v[24:25], v[20:21], v[192:193], v[158:159]
	v_pk_fma_f32 v[26:27], v[22:23], v[194:195], v[160:161]
	global_load_dwordx4 v[158:161], v[226:227], off
	global_load_dwordx4 v[192:195], v[230:231], off offset:3584
	s_waitcnt vmcnt(21)
	global_store_dwordx4 v[212:213], v[24:27], off
	v_pk_fma_f32 v[20:21], v[24:25], v[162:163], v[130:131]
	v_pk_fma_f32 v[22:23], v[26:27], v[164:165], v[132:133]
	s_waitcnt vmcnt(19)
	global_store_dwordx4 v[214:215], v[20:23], off
	v_pk_fma_f32 v[24:25], v[20:21], v[166:167], v[134:135]
	v_pk_fma_f32 v[26:27], v[22:23], v[168:169], v[136:137]
	s_waitcnt vmcnt(17)
	global_store_dwordx4 v[216:217], v[24:27], off
	v_pk_fma_f32 v[20:21], v[24:25], v[170:171], v[138:139]
	v_pk_fma_f32 v[22:23], v[26:27], v[172:173], v[140:141]
	s_waitcnt vmcnt(15)
	global_store_dwordx4 v[218:219], v[20:23], off
	v_pk_fma_f32 v[24:25], v[20:21], v[174:175], v[142:143]
	v_pk_fma_f32 v[26:27], v[22:23], v[176:177], v[144:145]
	s_waitcnt vmcnt(13)
	global_store_dwordx4 v[220:221], v[24:27], off
	v_pk_fma_f32 v[20:21], v[24:25], v[178:179], v[146:147]
	v_pk_fma_f32 v[22:23], v[26:27], v[180:181], v[148:149]
	s_waitcnt vmcnt(11)
	global_store_dwordx4 v[222:223], v[20:23], off
	v_pk_fma_f32 v[24:25], v[20:21], v[184:185], v[150:151]
	v_pk_fma_f32 v[26:27], v[22:23], v[186:187], v[152:153]
	s_waitcnt vmcnt(9)
	global_store_dwordx4 v[224:225], v[24:27], off
	v_pk_fma_f32 v[20:21], v[24:25], v[188:189], v[154:155]
	v_pk_fma_f32 v[22:23], v[26:27], v[190:191], v[156:157]
	s_waitcnt vmcnt(7)
	global_store_dwordx4 v[226:227], v[20:23], off
	v_pk_fma_f32 v[24:25], v[20:21], v[192:193], v[158:159]
	v_pk_fma_f32 v[26:27], v[22:23], v[194:195], v[160:161]
	s_nop 0
	global_store_dword v[4:5], v24, off
	global_store_dword v[4:5], v25, off offset:512
	global_store_dword v[4:5], v26, off offset:1024
	global_store_dword v[4:5], v27, off offset:1536
	s_andn2_b64 exec, exec, s[8:9]
	s_cbranch_execnz .LBB0_937
